# LRU depthwise conv phase rewritten: 8 columns (16 bytes) per lane, wave-uniform row/validity logic on the scalar unit, 24 loads in flight per trip
# baseline (speedup 1.0000x reference)
; #define INP(k) input_ptr(args, (k))
; __global__ void __launch_bounds__(NTHR, 2) fwd(Args args) {
;     ...
;                 const float* cw = INP(I_LCW); const float* cb = INP(I_LCB);
;                 const int c4 = (int)(gtid & 511) * 4, rstep = (int)(NGT >> 9);
;                 f32x4 cwv[4]; const f32x4 cbv = *(const f32x4*)(cb + c4);
; #pragma unroll
;                 for (int k = 0; k < 4; ++k) cwv[k] = *(const f32x4*)(cw + k * D + c4);
; #pragma unroll 1
;                 for (int row0 = (int)(gtid >> 9); row0 < R; row0 += 4 * rstep) {
;                     u32x2 tw[4][4]; int rws[4];
; #pragma unroll
;                     for (int j = 0; j < 4; ++j) { const int r = row0 + j * rstep; const int row = r < R ? r : row0; rws[j] = row;
;                         const int t = row < RL ? (row & (SEQ - 1)) : ((row - RL) & (CTX - 1)), len = row < RL ? SEQ : CTX;
; #pragma unroll
;                         for (int k = 0; k < 4; ++k) { const int tt = t + k - 2; const bool ok = tt >= 0 && tt < len; const u32x2 w = *(const u32x2*)(REC + (size_t)(ok ? row + k - 2 : row) * D + c4);
;                             tw[j][k] = ok ? w : (u32x2){0u, 0u}; } }
.LBB0_1267:
	v_readlane_b32 s2, v255, 14
	v_readlane_b32 s3, v255, 15
	s_andn2_b64 vcc, exec, s[2:3]
	s_cbranch_vccnz .LBB0_1357
	s_load_dword s20, s[86:87], 0x0
	v_mov_b32_e32 v0, 27
	s_waitcnt vmcnt(0)
	v_mov_b32_e32 v2, s96
	v_readfirstlane_b32 s6, v0
	s_waitcnt lgkmcnt(0)
	v_mov_b32_e32 v3, s20
	v_mbcnt_lo_u32_b32 v0, -1, 0
	v_mbcnt_hi_u32_b32 v0, -1, v0
	s_nop 0
	v_readfirstlane_b32 s3, v2
	v_mov_b32_e32 v2, 11
	v_or_b32_e32 v0, s97, v0
	v_readfirstlane_b32 s8, v2
	v_mov_b32_e32 v2, 12
	v_readfirstlane_b32 s10, v3
	v_readfirstlane_b32 s2, v2
	v_ashrrev_i32_e32 v2, 9, v0
	v_add_u32_e32 v26, s3, v2
	v_cmp_gt_i32_e32 vcc, s80, v26
	s_and_saveexec_b64 s[4:5], vcc
	s_cbranch_execz .LBB0_1303
	s_load_dwordx2 s[8:9], s[0:1], 0x58
	s_load_dwordx2 s[2:3], s[0:1], 0x60
	s_load_dwordx2 s[6:7], s[0:1], 0xd8
	v_and_b32_e32 v2, 0xff, v0
	v_lshlrev_b32_e32 v3, 5, v2
	v_lshlrev_b32_e32 v2, 4, v2
	s_waitcnt lgkmcnt(0)
	v_add_u32_e32 v4, 0x0, v3
	global_load_dwordx4 v[128:131], v4, s[8:9]
	global_load_dwordx4 v[132:135], v4, s[8:9] offset:16
	v_add_u32_e32 v4, 0x2000, v3
	global_load_dwordx4 v[136:139], v4, s[8:9]
	global_load_dwordx4 v[140:143], v4, s[8:9] offset:16
	v_add_u32_e32 v4, 0x4000, v3
	global_load_dwordx4 v[144:147], v4, s[8:9]
	global_load_dwordx4 v[148:151], v4, s[8:9] offset:16
	v_add_u32_e32 v4, 0x6000, v3
	global_load_dwordx4 v[152:155], v4, s[8:9]
	global_load_dwordx4 v[156:159], v4, s[8:9] offset:16
	global_load_dwordx4 v[160:163], v3, s[2:3]
	global_load_dwordx4 v[164:167], v3, s[2:3] offset:16
	s_add_u32 s10, s6, 0x27300000
	s_addc_u32 s11, s7, 0
	s_add_u32 s12, s6, 0x2bb00000
	s_addc_u32 s13, s7, 0
	s_lshr_b32 s14, s97, 8
	s_lshl_b32 s15, s96, 1
	s_add_i32 s15, s15, s14
	s_mov_b32 s26, 0x800
	s_mov_b32 s27, 0x100
	s_mov_b32 s28, 3
.Lconv_trip:
	s_cmp_lt_u32 s15, 0x2000
	s_cselect_b32 s18, s26, s27
	s_add_i32 s17, s18, -1
	s_and_b32 s17, s15, s17
	s_lshl_b32 s19, s15, 12
	v_add_u32_e32 v168, s19, v2
	s_cmp_ge_u32 s17, 2
	s_cbranch_scc0 .Lconv_z1
	v_add_u32_e32 v4, 0xffffe000, v168
	global_load_dwordx4 v[32:35], v4, s[10:11]
	s_branch .Lconv_n1
.Lconv_z1:
	v_mov_b32_e32 v32, 0
	v_mov_b32_e32 v33, 0
	v_mov_b32_e32 v34, 0
	v_mov_b32_e32 v35, 0
.Lconv_n1:
	s_cmp_ge_u32 s17, 1
	s_cbranch_scc0 .Lconv_z2
	v_add_u32_e32 v4, 0xfffff000, v168
	global_load_dwordx4 v[36:39], v4, s[10:11]
	s_branch .Lconv_n2
.Lconv_z2:
	v_mov_b32_e32 v36, 0
	v_mov_b32_e32 v37, 0
	v_mov_b32_e32 v38, 0
	v_mov_b32_e32 v39, 0
.Lconv_n2:
	v_add_u32_e32 v4, 0x0, v168
	global_load_dwordx4 v[40:43], v4, s[10:11]
	s_add_i32 s20, s17, 1
	s_cmp_lt_u32 s20, s18
	s_cbranch_scc0 .Lconv_z4
	v_add_u32_e32 v4, 0x1000, v168
	global_load_dwordx4 v[44:47], v4, s[10:11]
	s_branch .Lconv_n4
.Lconv_z4:
	v_mov_b32_e32 v44, 0
	v_mov_b32_e32 v45, 0
	v_mov_b32_e32 v46, 0
	v_mov_b32_e32 v47, 0
.Lconv_n4:
	s_addk_i32 s15, 0x200
	s_cmp_lt_u32 s15, 0x2000
	s_cselect_b32 s18, s26, s27
	s_add_i32 s17, s18, -1
	s_and_b32 s17, s15, s17
	s_lshl_b32 s19, s15, 12
	v_add_u32_e32 v169, s19, v2
	s_cmp_ge_u32 s17, 2
	s_cbranch_scc0 .Lconv_z5
	v_add_u32_e32 v4, 0xffffe000, v169
	global_load_dwordx4 v[48:51], v4, s[10:11]
	s_branch .Lconv_n5
.Lconv_z5:
	v_mov_b32_e32 v48, 0
	v_mov_b32_e32 v49, 0
	v_mov_b32_e32 v50, 0
	v_mov_b32_e32 v51, 0
.Lconv_n5:
	s_cmp_ge_u32 s17, 1
	s_cbranch_scc0 .Lconv_z6
	v_add_u32_e32 v4, 0xfffff000, v169
	global_load_dwordx4 v[52:55], v4, s[10:11]
	s_branch .Lconv_n6
.Lconv_z6:
	v_mov_b32_e32 v52, 0
	v_mov_b32_e32 v53, 0
	v_mov_b32_e32 v54, 0
	v_mov_b32_e32 v55, 0
.Lconv_n6:
	v_add_u32_e32 v4, 0x0, v169
	global_load_dwordx4 v[56:59], v4, s[10:11]
	s_add_i32 s20, s17, 1
	s_cmp_lt_u32 s20, s18
	s_cbranch_scc0 .Lconv_z8
	v_add_u32_e32 v4, 0x1000, v169
	global_load_dwordx4 v[60:63], v4, s[10:11]
	s_branch .Lconv_n8
.Lconv_z8:
	v_mov_b32_e32 v60, 0
	v_mov_b32_e32 v61, 0
	v_mov_b32_e32 v62, 0
	v_mov_b32_e32 v63, 0
.Lconv_n8:
	s_addk_i32 s15, 0x200
	s_cmp_lt_u32 s15, 0x2000
	s_cselect_b32 s18, s26, s27
	s_add_i32 s17, s18, -1
	s_and_b32 s17, s15, s17
	s_lshl_b32 s19, s15, 12
	v_add_u32_e32 v170, s19, v2
	s_cmp_ge_u32 s17, 2
	s_cbranch_scc0 .Lconv_z9
	v_add_u32_e32 v4, 0xffffe000, v170
	global_load_dwordx4 v[64:67], v4, s[10:11]
	s_branch .Lconv_n9
.Lconv_z9:
	v_mov_b32_e32 v64, 0
	v_mov_b32_e32 v65, 0
	v_mov_b32_e32 v66, 0
	v_mov_b32_e32 v67, 0
.Lconv_n9:
	s_cmp_ge_u32 s17, 1
	s_cbranch_scc0 .Lconv_z10
	v_add_u32_e32 v4, 0xfffff000, v170
	global_load_dwordx4 v[68:71], v4, s[10:11]
	s_branch .Lconv_n10
.Lconv_z10:
	v_mov_b32_e32 v68, 0
	v_mov_b32_e32 v69, 0
	v_mov_b32_e32 v70, 0
	v_mov_b32_e32 v71, 0
.Lconv_n10:
	v_add_u32_e32 v4, 0x0, v170
	global_load_dwordx4 v[72:75], v4, s[10:11]
	s_add_i32 s20, s17, 1
	s_cmp_lt_u32 s20, s18
	s_cbranch_scc0 .Lconv_z12
	v_add_u32_e32 v4, 0x1000, v170
	global_load_dwordx4 v[76:79], v4, s[10:11]
	s_branch .Lconv_n12
.Lconv_z12:
	v_mov_b32_e32 v76, 0
	v_mov_b32_e32 v77, 0
	v_mov_b32_e32 v78, 0
	v_mov_b32_e32 v79, 0
.Lconv_n12:
	s_addk_i32 s15, 0x200
	s_cmp_lt_u32 s15, 0x2000
	s_cselect_b32 s18, s26, s27
	s_add_i32 s17, s18, -1
	s_and_b32 s17, s15, s17
	s_lshl_b32 s19, s15, 12
	v_add_u32_e32 v171, s19, v2
	s_cmp_ge_u32 s17, 2
	s_cbranch_scc0 .Lconv_z13
	v_add_u32_e32 v4, 0xffffe000, v171
	global_load_dwordx4 v[80:83], v4, s[10:11]
	s_branch .Lconv_n13
.Lconv_z13:
	v_mov_b32_e32 v80, 0
	v_mov_b32_e32 v81, 0
	v_mov_b32_e32 v82, 0
	v_mov_b32_e32 v83, 0
.Lconv_n13:
	s_cmp_ge_u32 s17, 1
	s_cbranch_scc0 .Lconv_z14
	v_add_u32_e32 v4, 0xfffff000, v171
	global_load_dwordx4 v[84:87], v4, s[10:11]
	s_branch .Lconv_n14
.Lconv_z14:
	v_mov_b32_e32 v84, 0
	v_mov_b32_e32 v85, 0
	v_mov_b32_e32 v86, 0
	v_mov_b32_e32 v87, 0
; __device__ __forceinline__ u32x2 pk4(f32x4 v) { u32x2 w; w.x = cvt_pk_bf16(v[0], v[1]); w.y = cvt_pk_bf16(v[2], v[3]); return w; }
; __global__ void __launch_bounds__(NTHR, 2) fwd(Args args) {
;     ...
;                     for (int j = 0; j < 4; ++j) { const int r = row0 + j * rstep; const int row = r < R ? r : row0; rws[j] = row;
;                         const int t = row < RL ? (row & (SEQ - 1)) : ((row - RL) & (CTX - 1)), len = row < RL ? SEQ : CTX;
; #pragma unroll
;                         for (int k = 0; k < 4; ++k) { const int tt = t + k - 2; const bool ok = tt >= 0 && tt < len; const u32x2 w = *(const u32x2*)(REC + (size_t)(ok ? row + k - 2 : row) * D + c4);
;                             tw[j][k] = ok ? w : (u32x2){0u, 0u}; } }
; #pragma unroll
;                     for (int j = 0; j < 4; ++j) { f32x4 a = cbv;
; #pragma unroll
;                         for (int k = 0; k < 4; ++k) a += cwv[k] * (f32x4){__uint_as_float(tw[j][k].x << 16), __uint_as_float(tw[j][k].x & 0xffff0000u), __uint_as_float(tw[j][k].y << 16), __uint_as_float(tw[j][k].y & 0xffff0000u)};
;                         *(u32x2*)(XCB + (size_t)rws[j] * D + c4) = pk4(a); } }
.Lconv_n14:
	v_add_u32_e32 v4, 0x0, v171
	global_load_dwordx4 v[88:91], v4, s[10:11]
	s_add_i32 s20, s17, 1
	s_cmp_lt_u32 s20, s18
	s_cbranch_scc0 .Lconv_z16
	v_add_u32_e32 v4, 0x1000, v171
	global_load_dwordx4 v[92:95], v4, s[10:11]
	s_branch .Lconv_n16
.Lconv_z16:
	v_mov_b32_e32 v92, 0
	v_mov_b32_e32 v93, 0
	v_mov_b32_e32 v94, 0
	v_mov_b32_e32 v95, 0
.Lconv_n16:
	s_addk_i32 s15, 0x200
	s_cmp_lt_u32 s15, 0x2000
	s_cselect_b32 s18, s26, s27
	s_add_i32 s17, s18, -1
	s_and_b32 s17, s15, s17
	s_lshl_b32 s19, s15, 12
	v_add_u32_e32 v172, s19, v2
	s_cmp_ge_u32 s17, 2
	s_cbranch_scc0 .Lconv_z17
	v_add_u32_e32 v4, 0xffffe000, v172
	global_load_dwordx4 v[96:99], v4, s[10:11]
	s_branch .Lconv_n17
.Lconv_z17:
	v_mov_b32_e32 v96, 0
	v_mov_b32_e32 v97, 0
	v_mov_b32_e32 v98, 0
	v_mov_b32_e32 v99, 0
.Lconv_n17:
	s_cmp_ge_u32 s17, 1
	s_cbranch_scc0 .Lconv_z18
	v_add_u32_e32 v4, 0xfffff000, v172
	global_load_dwordx4 v[100:103], v4, s[10:11]
	s_branch .Lconv_n18
.Lconv_z18:
	v_mov_b32_e32 v100, 0
	v_mov_b32_e32 v101, 0
	v_mov_b32_e32 v102, 0
	v_mov_b32_e32 v103, 0
.Lconv_n18:
	v_add_u32_e32 v4, 0x0, v172
	global_load_dwordx4 v[104:107], v4, s[10:11]
	s_add_i32 s20, s17, 1
	s_cmp_lt_u32 s20, s18
	s_cbranch_scc0 .Lconv_z20
	v_add_u32_e32 v4, 0x1000, v172
	global_load_dwordx4 v[108:111], v4, s[10:11]
	s_branch .Lconv_n20
.Lconv_z20:
	v_mov_b32_e32 v108, 0
	v_mov_b32_e32 v109, 0
	v_mov_b32_e32 v110, 0
	v_mov_b32_e32 v111, 0
.Lconv_n20:
	s_addk_i32 s15, 0x200
	s_cmp_lt_u32 s15, 0x2000
	s_cselect_b32 s18, s26, s27
	s_add_i32 s17, s18, -1
	s_and_b32 s17, s15, s17
	s_lshl_b32 s19, s15, 12
	v_add_u32_e32 v173, s19, v2
	s_cmp_ge_u32 s17, 2
	s_cbranch_scc0 .Lconv_z21
	v_add_u32_e32 v4, 0xffffe000, v173
	global_load_dwordx4 v[112:115], v4, s[10:11]
	s_branch .Lconv_n21
.Lconv_z21:
	v_mov_b32_e32 v112, 0
	v_mov_b32_e32 v113, 0
	v_mov_b32_e32 v114, 0
	v_mov_b32_e32 v115, 0
.Lconv_n21:
	s_cmp_ge_u32 s17, 1
	s_cbranch_scc0 .Lconv_z22
	v_add_u32_e32 v4, 0xfffff000, v173
	global_load_dwordx4 v[116:119], v4, s[10:11]
	s_branch .Lconv_n22
.Lconv_z22:
	v_mov_b32_e32 v116, 0
	v_mov_b32_e32 v117, 0
	v_mov_b32_e32 v118, 0
	v_mov_b32_e32 v119, 0
.Lconv_n22:
	v_add_u32_e32 v4, 0x0, v173
	global_load_dwordx4 v[120:123], v4, s[10:11]
	s_add_i32 s20, s17, 1
	s_cmp_lt_u32 s20, s18
	s_cbranch_scc0 .Lconv_z24
	v_add_u32_e32 v4, 0x1000, v173
	global_load_dwordx4 v[124:127], v4, s[10:11]
	s_branch .Lconv_n24
.Lconv_z24:
	v_mov_b32_e32 v124, 0
	v_mov_b32_e32 v125, 0
	v_mov_b32_e32 v126, 0
	v_mov_b32_e32 v127, 0
.Lconv_n24:
	s_addk_i32 s15, 0x200
	s_waitcnt vmcnt(0)
	v_lshlrev_b32_e32 v184, 16, v32
	v_and_b32_e32 v185, 0xffff0000, v32
	v_lshlrev_b32_e32 v186, 16, v36
	v_and_b32_e32 v187, 0xffff0000, v36
	v_lshlrev_b32_e32 v188, 16, v40
	v_and_b32_e32 v189, 0xffff0000, v40
	v_lshlrev_b32_e32 v190, 16, v44
	v_and_b32_e32 v191, 0xffff0000, v44
	v_pk_fma_f32 v[176:177], v[128:129], v[184:185], v[160:161]
	v_pk_fma_f32 v[176:177], v[136:137], v[186:187], v[176:177]
	v_pk_fma_f32 v[176:177], v[144:145], v[188:189], v[176:177]
	v_pk_fma_f32 v[176:177], v[152:153], v[190:191], v[176:177]
	v_lshlrev_b32_e32 v184, 16, v33
	v_and_b32_e32 v185, 0xffff0000, v33
	v_lshlrev_b32_e32 v186, 16, v37
	v_and_b32_e32 v187, 0xffff0000, v37
	v_lshlrev_b32_e32 v188, 16, v41
	v_and_b32_e32 v189, 0xffff0000, v41
	v_lshlrev_b32_e32 v190, 16, v45
	v_and_b32_e32 v191, 0xffff0000, v45
	v_pk_fma_f32 v[178:179], v[130:131], v[184:185], v[162:163]
	v_pk_fma_f32 v[178:179], v[138:139], v[186:187], v[178:179]
	v_pk_fma_f32 v[178:179], v[146:147], v[188:189], v[178:179]
	v_pk_fma_f32 v[178:179], v[154:155], v[190:191], v[178:179]
	v_lshlrev_b32_e32 v184, 16, v34
	v_and_b32_e32 v185, 0xffff0000, v34
	v_lshlrev_b32_e32 v186, 16, v38
	v_and_b32_e32 v187, 0xffff0000, v38
	v_lshlrev_b32_e32 v188, 16, v42
	v_and_b32_e32 v189, 0xffff0000, v42
	v_lshlrev_b32_e32 v190, 16, v46
	v_and_b32_e32 v191, 0xffff0000, v46
	v_pk_fma_f32 v[180:181], v[132:133], v[184:185], v[164:165]
	v_pk_fma_f32 v[180:181], v[140:141], v[186:187], v[180:181]
	v_pk_fma_f32 v[180:181], v[148:149], v[188:189], v[180:181]
	v_pk_fma_f32 v[180:181], v[156:157], v[190:191], v[180:181]
	v_lshlrev_b32_e32 v184, 16, v35
	v_and_b32_e32 v185, 0xffff0000, v35
	v_lshlrev_b32_e32 v186, 16, v39
	v_and_b32_e32 v187, 0xffff0000, v39
	v_lshlrev_b32_e32 v188, 16, v43
	v_and_b32_e32 v189, 0xffff0000, v43
	v_lshlrev_b32_e32 v190, 16, v47
	v_and_b32_e32 v191, 0xffff0000, v47
	v_pk_fma_f32 v[182:183], v[134:135], v[184:185], v[166:167]
	v_pk_fma_f32 v[182:183], v[142:143], v[186:187], v[182:183]
	v_pk_fma_f32 v[182:183], v[150:151], v[188:189], v[182:183]
	v_pk_fma_f32 v[182:183], v[158:159], v[190:191], v[182:183]
	v_cvt_pk_bf16_f32 v192, v176, v177
	v_cvt_pk_bf16_f32 v193, v178, v179
	v_cvt_pk_bf16_f32 v194, v180, v181
	v_cvt_pk_bf16_f32 v195, v182, v183
	global_store_dwordx4 v168, v[192:195], s[12:13]
	s_nop 1
	v_lshlrev_b32_e32 v184, 16, v48
	v_and_b32_e32 v185, 0xffff0000, v48
	v_lshlrev_b32_e32 v186, 16, v52
	v_and_b32_e32 v187, 0xffff0000, v52
	v_lshlrev_b32_e32 v188, 16, v56
	v_and_b32_e32 v189, 0xffff0000, v56
	v_lshlrev_b32_e32 v190, 16, v60
	v_and_b32_e32 v191, 0xffff0000, v60
	v_pk_fma_f32 v[176:177], v[128:129], v[184:185], v[160:161]
	v_pk_fma_f32 v[176:177], v[136:137], v[186:187], v[176:177]
	v_pk_fma_f32 v[176:177], v[144:145], v[188:189], v[176:177]
	v_pk_fma_f32 v[176:177], v[152:153], v[190:191], v[176:177]
	v_lshlrev_b32_e32 v184, 16, v49
	v_and_b32_e32 v185, 0xffff0000, v49
	v_lshlrev_b32_e32 v186, 16, v53
	v_and_b32_e32 v187, 0xffff0000, v53
	v_lshlrev_b32_e32 v188, 16, v57
	v_and_b32_e32 v189, 0xffff0000, v57
	v_lshlrev_b32_e32 v190, 16, v61
; __device__ __forceinline__ u32x2 pk4(f32x4 v) { u32x2 w; w.x = cvt_pk_bf16(v[0], v[1]); w.y = cvt_pk_bf16(v[2], v[3]); return w; }
; __global__ void __launch_bounds__(NTHR, 2) fwd(Args args) {
;     ...
;                     for (int j = 0; j < 4; ++j) { f32x4 a = cbv;
; #pragma unroll
;                         for (int k = 0; k < 4; ++k) a += cwv[k] * (f32x4){__uint_as_float(tw[j][k].x << 16), __uint_as_float(tw[j][k].x & 0xffff0000u), __uint_as_float(tw[j][k].y << 16), __uint_as_float(tw[j][k].y & 0xffff0000u)};
;                         *(u32x2*)(XCB + (size_t)rws[j] * D + c4) = pk4(a); } }
	v_and_b32_e32 v191, 0xffff0000, v61
	v_pk_fma_f32 v[178:179], v[130:131], v[184:185], v[162:163]
	v_pk_fma_f32 v[178:179], v[138:139], v[186:187], v[178:179]
	v_pk_fma_f32 v[178:179], v[146:147], v[188:189], v[178:179]
	v_pk_fma_f32 v[178:179], v[154:155], v[190:191], v[178:179]
	v_lshlrev_b32_e32 v184, 16, v50
	v_and_b32_e32 v185, 0xffff0000, v50
	v_lshlrev_b32_e32 v186, 16, v54
	v_and_b32_e32 v187, 0xffff0000, v54
	v_lshlrev_b32_e32 v188, 16, v58
	v_and_b32_e32 v189, 0xffff0000, v58
	v_lshlrev_b32_e32 v190, 16, v62
	v_and_b32_e32 v191, 0xffff0000, v62
	v_pk_fma_f32 v[180:181], v[132:133], v[184:185], v[164:165]
	v_pk_fma_f32 v[180:181], v[140:141], v[186:187], v[180:181]
	v_pk_fma_f32 v[180:181], v[148:149], v[188:189], v[180:181]
	v_pk_fma_f32 v[180:181], v[156:157], v[190:191], v[180:181]
	v_lshlrev_b32_e32 v184, 16, v51
	v_and_b32_e32 v185, 0xffff0000, v51
	v_lshlrev_b32_e32 v186, 16, v55
	v_and_b32_e32 v187, 0xffff0000, v55
	v_lshlrev_b32_e32 v188, 16, v59
	v_and_b32_e32 v189, 0xffff0000, v59
	v_lshlrev_b32_e32 v190, 16, v63
	v_and_b32_e32 v191, 0xffff0000, v63
	v_pk_fma_f32 v[182:183], v[134:135], v[184:185], v[166:167]
	v_pk_fma_f32 v[182:183], v[142:143], v[186:187], v[182:183]
	v_pk_fma_f32 v[182:183], v[150:151], v[188:189], v[182:183]
	v_pk_fma_f32 v[182:183], v[158:159], v[190:191], v[182:183]
	v_cvt_pk_bf16_f32 v192, v176, v177
	v_cvt_pk_bf16_f32 v193, v178, v179
	v_cvt_pk_bf16_f32 v194, v180, v181
	v_cvt_pk_bf16_f32 v195, v182, v183
	global_store_dwordx4 v169, v[192:195], s[12:13]
	s_nop 1
	v_lshlrev_b32_e32 v184, 16, v64
	v_and_b32_e32 v185, 0xffff0000, v64
	v_lshlrev_b32_e32 v186, 16, v68
	v_and_b32_e32 v187, 0xffff0000, v68
	v_lshlrev_b32_e32 v188, 16, v72
	v_and_b32_e32 v189, 0xffff0000, v72
	v_lshlrev_b32_e32 v190, 16, v76
	v_and_b32_e32 v191, 0xffff0000, v76
	v_pk_fma_f32 v[176:177], v[128:129], v[184:185], v[160:161]
	v_pk_fma_f32 v[176:177], v[136:137], v[186:187], v[176:177]
	v_pk_fma_f32 v[176:177], v[144:145], v[188:189], v[176:177]
	v_pk_fma_f32 v[176:177], v[152:153], v[190:191], v[176:177]
	v_lshlrev_b32_e32 v184, 16, v65
	v_and_b32_e32 v185, 0xffff0000, v65
	v_lshlrev_b32_e32 v186, 16, v69
	v_and_b32_e32 v187, 0xffff0000, v69
	v_lshlrev_b32_e32 v188, 16, v73
	v_and_b32_e32 v189, 0xffff0000, v73
	v_lshlrev_b32_e32 v190, 16, v77
	v_and_b32_e32 v191, 0xffff0000, v77
	v_pk_fma_f32 v[178:179], v[130:131], v[184:185], v[162:163]
	v_pk_fma_f32 v[178:179], v[138:139], v[186:187], v[178:179]
	v_pk_fma_f32 v[178:179], v[146:147], v[188:189], v[178:179]
	v_pk_fma_f32 v[178:179], v[154:155], v[190:191], v[178:179]
	v_lshlrev_b32_e32 v184, 16, v66
	v_and_b32_e32 v185, 0xffff0000, v66
	v_lshlrev_b32_e32 v186, 16, v70
	v_and_b32_e32 v187, 0xffff0000, v70
	v_lshlrev_b32_e32 v188, 16, v74
	v_and_b32_e32 v189, 0xffff0000, v74
	v_lshlrev_b32_e32 v190, 16, v78
	v_and_b32_e32 v191, 0xffff0000, v78
	v_pk_fma_f32 v[180:181], v[132:133], v[184:185], v[164:165]
	v_pk_fma_f32 v[180:181], v[140:141], v[186:187], v[180:181]
	v_pk_fma_f32 v[180:181], v[148:149], v[188:189], v[180:181]
	v_pk_fma_f32 v[180:181], v[156:157], v[190:191], v[180:181]
	v_lshlrev_b32_e32 v184, 16, v67
	v_and_b32_e32 v185, 0xffff0000, v67
	v_lshlrev_b32_e32 v186, 16, v71
	v_and_b32_e32 v187, 0xffff0000, v71
	v_lshlrev_b32_e32 v188, 16, v75
	v_and_b32_e32 v189, 0xffff0000, v75
	v_lshlrev_b32_e32 v190, 16, v79
	v_and_b32_e32 v191, 0xffff0000, v79
	v_pk_fma_f32 v[182:183], v[134:135], v[184:185], v[166:167]
	v_pk_fma_f32 v[182:183], v[142:143], v[186:187], v[182:183]
	v_pk_fma_f32 v[182:183], v[150:151], v[188:189], v[182:183]
	v_pk_fma_f32 v[182:183], v[158:159], v[190:191], v[182:183]
	v_cvt_pk_bf16_f32 v192, v176, v177
	v_cvt_pk_bf16_f32 v193, v178, v179
	v_cvt_pk_bf16_f32 v194, v180, v181
	v_cvt_pk_bf16_f32 v195, v182, v183
	global_store_dwordx4 v170, v[192:195], s[12:13]
	s_nop 1
	v_lshlrev_b32_e32 v184, 16, v80
	v_and_b32_e32 v185, 0xffff0000, v80
	v_lshlrev_b32_e32 v186, 16, v84
	v_and_b32_e32 v187, 0xffff0000, v84
	v_lshlrev_b32_e32 v188, 16, v88
	v_and_b32_e32 v189, 0xffff0000, v88
	v_lshlrev_b32_e32 v190, 16, v92
	v_and_b32_e32 v191, 0xffff0000, v92
	v_pk_fma_f32 v[176:177], v[128:129], v[184:185], v[160:161]
	v_pk_fma_f32 v[176:177], v[136:137], v[186:187], v[176:177]
	v_pk_fma_f32 v[176:177], v[144:145], v[188:189], v[176:177]
	v_pk_fma_f32 v[176:177], v[152:153], v[190:191], v[176:177]
	v_lshlrev_b32_e32 v184, 16, v81
	v_and_b32_e32 v185, 0xffff0000, v81
	v_lshlrev_b32_e32 v186, 16, v85
	v_and_b32_e32 v187, 0xffff0000, v85
	v_lshlrev_b32_e32 v188, 16, v89
	v_and_b32_e32 v189, 0xffff0000, v89
	v_lshlrev_b32_e32 v190, 16, v93
	v_and_b32_e32 v191, 0xffff0000, v93
	v_pk_fma_f32 v[178:179], v[130:131], v[184:185], v[162:163]
	v_pk_fma_f32 v[178:179], v[138:139], v[186:187], v[178:179]
	v_pk_fma_f32 v[178:179], v[146:147], v[188:189], v[178:179]
	v_pk_fma_f32 v[178:179], v[154:155], v[190:191], v[178:179]
	v_lshlrev_b32_e32 v184, 16, v82
	v_and_b32_e32 v185, 0xffff0000, v82
	v_lshlrev_b32_e32 v186, 16, v86
	v_and_b32_e32 v187, 0xffff0000, v86
	v_lshlrev_b32_e32 v188, 16, v90
	v_and_b32_e32 v189, 0xffff0000, v90
	v_lshlrev_b32_e32 v190, 16, v94
	v_and_b32_e32 v191, 0xffff0000, v94
	v_pk_fma_f32 v[180:181], v[132:133], v[184:185], v[164:165]
	v_pk_fma_f32 v[180:181], v[140:141], v[186:187], v[180:181]
	v_pk_fma_f32 v[180:181], v[148:149], v[188:189], v[180:181]
	v_pk_fma_f32 v[180:181], v[156:157], v[190:191], v[180:181]
	v_lshlrev_b32_e32 v184, 16, v83
; __device__ __forceinline__ u32x2 pk4(f32x4 v) { u32x2 w; w.x = cvt_pk_bf16(v[0], v[1]); w.y = cvt_pk_bf16(v[2], v[3]); return w; }
; __global__ void __launch_bounds__(NTHR, 2) fwd(Args args) {
;     ...
;                     for (int j = 0; j < 4; ++j) { f32x4 a = cbv;
; #pragma unroll
;                         for (int k = 0; k < 4; ++k) a += cwv[k] * (f32x4){__uint_as_float(tw[j][k].x << 16), __uint_as_float(tw[j][k].x & 0xffff0000u), __uint_as_float(tw[j][k].y << 16), __uint_as_float(tw[j][k].y & 0xffff0000u)};
;                         *(u32x2*)(XCB + (size_t)rws[j] * D + c4) = pk4(a); } }
	v_and_b32_e32 v185, 0xffff0000, v83
	v_lshlrev_b32_e32 v186, 16, v87
	v_and_b32_e32 v187, 0xffff0000, v87
	v_lshlrev_b32_e32 v188, 16, v91
	v_and_b32_e32 v189, 0xffff0000, v91
	v_lshlrev_b32_e32 v190, 16, v95
	v_and_b32_e32 v191, 0xffff0000, v95
	v_pk_fma_f32 v[182:183], v[134:135], v[184:185], v[166:167]
	v_pk_fma_f32 v[182:183], v[142:143], v[186:187], v[182:183]
	v_pk_fma_f32 v[182:183], v[150:151], v[188:189], v[182:183]
	v_pk_fma_f32 v[182:183], v[158:159], v[190:191], v[182:183]
	v_cvt_pk_bf16_f32 v192, v176, v177
	v_cvt_pk_bf16_f32 v193, v178, v179
	v_cvt_pk_bf16_f32 v194, v180, v181
	v_cvt_pk_bf16_f32 v195, v182, v183
	global_store_dwordx4 v171, v[192:195], s[12:13]
	s_nop 1
	v_lshlrev_b32_e32 v184, 16, v96
	v_and_b32_e32 v185, 0xffff0000, v96
	v_lshlrev_b32_e32 v186, 16, v100
	v_and_b32_e32 v187, 0xffff0000, v100
	v_lshlrev_b32_e32 v188, 16, v104
	v_and_b32_e32 v189, 0xffff0000, v104
	v_lshlrev_b32_e32 v190, 16, v108
	v_and_b32_e32 v191, 0xffff0000, v108
	v_pk_fma_f32 v[176:177], v[128:129], v[184:185], v[160:161]
	v_pk_fma_f32 v[176:177], v[136:137], v[186:187], v[176:177]
	v_pk_fma_f32 v[176:177], v[144:145], v[188:189], v[176:177]
	v_pk_fma_f32 v[176:177], v[152:153], v[190:191], v[176:177]
	v_lshlrev_b32_e32 v184, 16, v97
	v_and_b32_e32 v185, 0xffff0000, v97
	v_lshlrev_b32_e32 v186, 16, v101
	v_and_b32_e32 v187, 0xffff0000, v101
	v_lshlrev_b32_e32 v188, 16, v105
	v_and_b32_e32 v189, 0xffff0000, v105
	v_lshlrev_b32_e32 v190, 16, v109
	v_and_b32_e32 v191, 0xffff0000, v109
	v_pk_fma_f32 v[178:179], v[130:131], v[184:185], v[162:163]
	v_pk_fma_f32 v[178:179], v[138:139], v[186:187], v[178:179]
	v_pk_fma_f32 v[178:179], v[146:147], v[188:189], v[178:179]
	v_pk_fma_f32 v[178:179], v[154:155], v[190:191], v[178:179]
	v_lshlrev_b32_e32 v184, 16, v98
	v_and_b32_e32 v185, 0xffff0000, v98
	v_lshlrev_b32_e32 v186, 16, v102
	v_and_b32_e32 v187, 0xffff0000, v102
	v_lshlrev_b32_e32 v188, 16, v106
	v_and_b32_e32 v189, 0xffff0000, v106
	v_lshlrev_b32_e32 v190, 16, v110
	v_and_b32_e32 v191, 0xffff0000, v110
	v_pk_fma_f32 v[180:181], v[132:133], v[184:185], v[164:165]
	v_pk_fma_f32 v[180:181], v[140:141], v[186:187], v[180:181]
	v_pk_fma_f32 v[180:181], v[148:149], v[188:189], v[180:181]
	v_pk_fma_f32 v[180:181], v[156:157], v[190:191], v[180:181]
	v_lshlrev_b32_e32 v184, 16, v99
	v_and_b32_e32 v185, 0xffff0000, v99
	v_lshlrev_b32_e32 v186, 16, v103
	v_and_b32_e32 v187, 0xffff0000, v103
	v_lshlrev_b32_e32 v188, 16, v107
	v_and_b32_e32 v189, 0xffff0000, v107
	v_lshlrev_b32_e32 v190, 16, v111
	v_and_b32_e32 v191, 0xffff0000, v111
	v_pk_fma_f32 v[182:183], v[134:135], v[184:185], v[166:167]
	v_pk_fma_f32 v[182:183], v[142:143], v[186:187], v[182:183]
	v_pk_fma_f32 v[182:183], v[150:151], v[188:189], v[182:183]
	v_pk_fma_f32 v[182:183], v[158:159], v[190:191], v[182:183]
	v_cvt_pk_bf16_f32 v192, v176, v177
	v_cvt_pk_bf16_f32 v193, v178, v179
	v_cvt_pk_bf16_f32 v194, v180, v181
	v_cvt_pk_bf16_f32 v195, v182, v183
	global_store_dwordx4 v172, v[192:195], s[12:13]
	s_nop 1
	v_lshlrev_b32_e32 v184, 16, v112
	v_and_b32_e32 v185, 0xffff0000, v112
	v_lshlrev_b32_e32 v186, 16, v116
	v_and_b32_e32 v187, 0xffff0000, v116
	v_lshlrev_b32_e32 v188, 16, v120
	v_and_b32_e32 v189, 0xffff0000, v120
	v_lshlrev_b32_e32 v190, 16, v124
	v_and_b32_e32 v191, 0xffff0000, v124
	v_pk_fma_f32 v[176:177], v[128:129], v[184:185], v[160:161]
	v_pk_fma_f32 v[176:177], v[136:137], v[186:187], v[176:177]
	v_pk_fma_f32 v[176:177], v[144:145], v[188:189], v[176:177]
	v_pk_fma_f32 v[176:177], v[152:153], v[190:191], v[176:177]
	v_lshlrev_b32_e32 v184, 16, v113
	v_and_b32_e32 v185, 0xffff0000, v113
	v_lshlrev_b32_e32 v186, 16, v117
	v_and_b32_e32 v187, 0xffff0000, v117
	v_lshlrev_b32_e32 v188, 16, v121
	v_and_b32_e32 v189, 0xffff0000, v121
	v_lshlrev_b32_e32 v190, 16, v125
	v_and_b32_e32 v191, 0xffff0000, v125
	v_pk_fma_f32 v[178:179], v[130:131], v[184:185], v[162:163]
	v_pk_fma_f32 v[178:179], v[138:139], v[186:187], v[178:179]
	v_pk_fma_f32 v[178:179], v[146:147], v[188:189], v[178:179]
	v_pk_fma_f32 v[178:179], v[154:155], v[190:191], v[178:179]
	v_lshlrev_b32_e32 v184, 16, v114
	v_and_b32_e32 v185, 0xffff0000, v114
	v_lshlrev_b32_e32 v186, 16, v118
	v_and_b32_e32 v187, 0xffff0000, v118
	v_lshlrev_b32_e32 v188, 16, v122
	v_and_b32_e32 v189, 0xffff0000, v122
	v_lshlrev_b32_e32 v190, 16, v126
	v_and_b32_e32 v191, 0xffff0000, v126
	v_pk_fma_f32 v[180:181], v[132:133], v[184:185], v[164:165]
	v_pk_fma_f32 v[180:181], v[140:141], v[186:187], v[180:181]
	v_pk_fma_f32 v[180:181], v[148:149], v[188:189], v[180:181]
	v_pk_fma_f32 v[180:181], v[156:157], v[190:191], v[180:181]
	v_lshlrev_b32_e32 v184, 16, v115
	v_and_b32_e32 v185, 0xffff0000, v115
	v_lshlrev_b32_e32 v186, 16, v119
	v_and_b32_e32 v187, 0xffff0000, v119
	v_lshlrev_b32_e32 v188, 16, v123
	v_and_b32_e32 v189, 0xffff0000, v123
	v_lshlrev_b32_e32 v190, 16, v127
	v_and_b32_e32 v191, 0xffff0000, v127
	v_pk_fma_f32 v[182:183], v[134:135], v[184:185], v[166:167]
	v_pk_fma_f32 v[182:183], v[142:143], v[186:187], v[182:183]
	v_pk_fma_f32 v[182:183], v[150:151], v[188:189], v[182:183]
	v_pk_fma_f32 v[182:183], v[158:159], v[190:191], v[182:183]
	v_cvt_pk_bf16_f32 v192, v176, v177
	v_cvt_pk_bf16_f32 v193, v178, v179
	v_cvt_pk_bf16_f32 v194, v180, v181
	v_cvt_pk_bf16_f32 v195, v182, v183
	global_store_dwordx4 v173, v[192:195], s[12:13]
	s_nop 1
	s_sub_i32 s28, s28, 1
	s_cmp_lg_u32 s28, 0
	s_cbranch_scc1 .Lconv_trip
